# baseline (speedup 1.0000x reference)
; __device__ void attn_item(const Params& p, int item, u16* O) {
;   const int tid = tid_(), wid = tid >> 6, lane = tid & 63, fr = lane & 15, g4 = lane >> 4;
;   const int qt = item & 63, hh = (item >> 6) & 15, b = item >> 10;
;   const u16* Q = (const u16*)(p.ws + OFF_Q);
;   const u16* Kg = (const u16*)(p.ws + OFF_K);
;   const u16* Vg = (const u16*)(p.ws + OFF_V);
;   u16* Ks = (u16*)g_shm;
;   u16* Vt = (u16*)(g_shm + 17408);
;   int* flags = (int*)(g_shm + 17408 + 18432);
;   const size_t tb = (size_t)b * SEQ;
;   const int q0 = qt * 128;
;   const int qrow = q0 + wid * 16 + fr;
;   bf16x8 qf[4];
; #pragma unroll
;   for (int ks = 0; ks < 4; ++ks) qf[ks] = *(const bf16x8*)(Q + (tb + qrow) * DM + hh * 128 + ks * 32 + g4 * 8);
;   f32x4 o[8];
; #pragma unroll
;   for (int i = 0; i < 8; ++i) o[i] = f32x4{0.f, 0.f, 0.f, 0.f};
;   float R = 0.f;
;   if (tid < 8) flags[tid] = 0;
;   const int kt0 = (q0 + 128) / 64 - 1;
;   i32x4 rK[2];
;   bf16x8 rV[2];
;   auto load_kv = [&](int kt) {
; #pragma unroll
;     for (int i = 0; i < 2; ++i) {
;       int idx = tid + i * NT;
;       rK[i] = *(const i32x4*)(Kg + (tb + kt * 64 + (idx >> 4)) * DM + hh * 128 + (idx & 15) * 8);
;       rV[i] = *(const bf16x8*)(Vg + (tb + kt * 64 + (idx & 63)) * DM + hh * 128 + (idx >> 6) * 8);
;     }
;   };
;   load_kv(kt0);
.LBB0_735:
	v_mov_b32_e32 v107, v81
	s_mov_b32 s98, 0
	s_ashr_i32 s0, s10, 10
	s_ashr_i32 s1, s0, 31
	v_mov_b32_e32 v30, v214
	s_lshl_b64 s[66:67], s[0:1], 13
	s_lshl_b32 s0, s10, 7
	s_and_b32 s3, s0, 0x1f80
	v_ashrrev_i32_e32 v29, 6, v30
	v_and_b32_e32 v28, 15, v30
	v_lshl_add_u32 v108, v29, 4, s3
	v_or_b32_e32 v82, v108, v28
	v_ashrrev_i32_e32 v83, 31, v82
	v_lshl_add_u64 v[0:1], s[66:67], 0, v[82:83]
	s_lshl_b32 s0, s10, 1
	v_lshlrev_b64 v[0:1], 12, v[0:1]
	s_and_b32 s0, s0, 0x780
	v_lshl_add_u64 v[0:1], s[58:59], 0, v[0:1]
	s_lshl_b32 s64, s0, 1
	v_lshl_add_u64 v[84:85], v[0:1], 0, s[64:65]
	v_and_b32_e32 v80, 48, v30
	s_waitcnt vmcnt(11)
	v_lshl_add_u64 v[16:17], v[84:85], 0, v[80:81]
	global_load_dwordx4 v[0:3], v[16:17], off
	global_load_dwordx4 v[4:7], v[16:17], off offset:64
	global_load_dwordx4 v[8:11], v[16:17], off offset:128
	global_load_dwordx4 v[12:15], v[16:17], off offset:192
	v_cmp_gt_i32_e32 vcc, 8, v30
	s_and_saveexec_b64 s[0:1], vcc
	v_lshlrev_b32_e32 v16, 2, v30
	ds_write_b32 v16, v81 offset:35840
	s_or_b64 exec, exec, s[0:1]
	s_add_i32 s4, s3, 64
	v_ashrrev_i32_e32 v32, 4, v30
	s_add_u32 s0, s66, s4
	v_ashrrev_i32_e32 v33, 31, v32
	s_addc_u32 s1, s67, 0
	v_lshl_add_u64 v[16:17], s[0:1], 0, v[32:33]
	v_lshlrev_b64 v[16:17], 12, v[16:17]
	v_lshl_add_u64 v[16:17], s[60:61], 0, v[16:17]
	v_lshlrev_b32_e32 v18, 4, v30
	v_and_b32_e32 v83, 63, v30
	v_lshl_add_u64 v[16:17], v[16:17], 0, s[64:65]
	v_and_b32_e32 v34, 0xf0, v18
	v_mov_b32_e32 v35, v81
	s_waitcnt vmcnt(13)
	v_lshl_add_u64 v[24:25], v[16:17], 0, v[34:35]
	v_or_b32_e32 v16, s4, v83
	v_mov_b32_e32 v17, v81
	v_lshl_add_u64 v[16:17], s[66:67], 0, v[16:17]
	v_lshlrev_b64 v[16:17], 12, v[16:17]
	v_ashrrev_i32_e32 v31, 3, v30
	v_lshl_add_u64 v[16:17], s[62:63], 0, v[16:17]
	v_and_b32_e32 v86, -8, v31
	v_lshl_add_u64 v[26:27], v[16:17], 0, s[64:65]
	v_ashrrev_i32_e32 v87, 31, v86
	s_waitcnt vmcnt(12)
	v_lshl_add_u64 v[36:37], v[86:87], 1, v[26:27]
	global_load_dwordx4 v[16:19], v[24:25], off
	global_load_dwordx4 v[20:23], v[36:37], off
	v_add_u32_e32 v36, 0x200, v30
	v_ashrrev_i32_e32 v40, 4, v36
	v_ashrrev_i32_e32 v41, 31, v40
	v_lshl_add_u64 v[24:25], s[0:1], 0, v[40:41]
	v_lshlrev_b64 v[24:25], 12, v[24:25]
	v_lshl_add_u64 v[24:25], s[60:61], 0, v[24:25]
	v_ashrrev_i32_e32 v46, 3, v36
	v_lshl_add_u64 v[24:25], v[24:25], 0, s[64:65]
	v_and_b32_e32 v88, -8, v46
	v_lshl_add_u64 v[42:43], v[24:25], 0, v[34:35]
	v_ashrrev_i32_e32 v89, 31, v88
	v_lshl_add_u64 v[44:45], v[88:89], 1, v[26:27]
	global_load_dwordx4 v[24:27], v[42:43], off
	global_load_dwordx4 v[36:39], v[44:45], off
	s_add_u32 s0, s60, s64
	v_bfe_u32 v30, v30, 4, 2
	s_addc_u32 s1, s61, 0
	v_lshl_add_u64 v[92:93], s[66:67], 0, v[32:33]
	v_lshl_add_u64 v[94:95], s[66:67], 0, v[40:41]
	v_lshlrev_b32_e32 v110, 2, v29
	v_mul_lo_u32 v29, v32, s74
	v_or_b32_e32 v31, 7, v31
	v_mul_lo_u32 v32, v40, s74
	v_or_b32_e32 v40, 7, v46
	v_lshlrev_b32_e32 v42, 3, v30
	v_lshl_add_u64 v[90:91], s[0:1], 0, v[34:35]
	v_lshlrev_b32_e32 v35, 1, v83
	v_lshlrev_b32_e32 v109, 2, v30
	v_cmp_eq_u32_e64 s[6:7], 1, v30
	v_cmp_eq_u32_e64 s[8:9], 2, v30
	v_mul_lo_u32 v30, v86, s75
	v_mul_lo_u32 v31, v31, s75
	v_mul_lo_u32 v33, v88, s75
	v_mul_lo_u32 v40, v40, s75
	v_mul_u32_u24_e32 v41, 0x110, v28
	v_mul_u32_u24_e32 v28, 0x90, v28
	v_mov_b32_e32 v44, v81
	v_mov_b32_e32 v45, v81
	v_mov_b32_e32 v46, v81
	v_mov_b32_e32 v47, v81
	s_add_u32 s68, s62, s64
	v_add_u32_e32 v111, v34, v29
	v_add_u32_e32 v112, v35, v30
	v_add_u32_e32 v114, v35, v31
	v_add_u32_e32 v115, v34, v32
	v_add_u32_e32 v116, v35, v33
	v_add_u32_e32 v117, v35, v40
	v_add_u32_e32 v118, v80, v41
	v_add_u32_e32 v119, v42, v28
	v_mov_b64_e32 v[62:63], v[46:47]
	v_mov_b64_e32 v[58:59], v[46:47]
	v_mov_b64_e32 v[54:55], v[46:47]
	v_mov_b64_e32 v[50:51], v[46:47]
	v_mov_b64_e32 v[40:41], v[44:45]
	v_mov_b64_e32 v[32:33], v[44:45]
	v_mov_b64_e32 v[28:29], v[44:45]
	s_addc_u32 s69, s63, 0
	v_cmp_gt_u32_e64 s[4:5], 16, v83
	v_cmp_eq_u32_e64 s[10:11], 0, v83
	v_mov_b32_e32 v113, 0
	s_mov_b32 s64, s3
	v_mov_b64_e32 v[60:61], v[44:45]
	v_mov_b64_e32 v[56:57], v[44:45]
	v_mov_b64_e32 v[52:53], v[44:45]
	v_mov_b64_e32 v[48:49], v[44:45]
	v_mov_b64_e32 v[42:43], v[46:47]
	v_mov_b64_e32 v[34:35], v[46:47]
	v_mov_b64_e32 v[30:31], v[46:47]
	s_branch .LBB0_743

; #define RAW_BARRIER()                                   \
;   do {                                                  \
;     asm volatile("s_waitcnt lgkmcnt(0)" ::: "memory");  \
;     __builtin_amdgcn_s_barrier();                       \
;     asm volatile("" ::: "memory");                      \
;   } while (0)
; __device__ void attn_item(const Params& p, int item, u16* O) {
;     ...
;     RAW_BARRIER();
;     {
;       bool done = true;
; #pragma unroll
;       for (int i = 0; i < 8; ++i) done = done && (flags[i] != 0);
;       if (done) break;
;     }
; #pragma unroll
;     for (int i = 0; i < 2; ++i) {
;       int idx = tid + i * NT;
;       *(i32x4*)(Ks + (idx >> 4) * 136 + (idx & 15) * 8) = rK[i];
;       int c8 = idx >> 6, key = idx & 63;
; #pragma unroll
;       for (int e = 0; e < 8; ++e) Vt[(c8 * 8 + e) * 72 + key] = (u16)rV[i][e];
;     }
;     if (kt > 0) load_kv(kt - 1);
.LBB0_743:
	s_waitcnt lgkmcnt(0)
	s_barrier
	ds_read_b128 v[64:67], v81 offset:35856
	ds_read_b128 v[68:71], v81 offset:35840
	s_waitcnt lgkmcnt(1)
	v_cmp_eq_u32_e32 vcc, 0, v66
	s_nop 1
	v_cndmask_b32_e64 v66, 0, 1, vcc
	v_cmp_eq_u32_e32 vcc, 0, v67
	v_lshlrev_b32_e32 v66, 2, v66
	s_nop 0
	v_cndmask_b32_e64 v67, 0, 1, vcc
	v_cmp_eq_u32_e32 vcc, 0, v65
	v_lshlrev_b32_e32 v67, 3, v67
	v_or_b32_e32 v66, v67, v66
	v_cndmask_b32_e64 v65, 0, 1, vcc
	v_cmp_eq_u32_e32 vcc, 0, v64
	v_lshlrev_b32_e32 v65, 1, v65
	s_nop 0
	v_cndmask_b32_e64 v64, 0, 1, vcc
	v_or_b32_e32 v64, v64, v65
	s_waitcnt lgkmcnt(0)
	v_cmp_eq_u32_e32 vcc, 0, v70
	v_and_b32_e32 v64, 3, v64
	v_or_b32_e32 v64, v64, v66
	v_cndmask_b32_e64 v65, 0, 1, vcc
	v_cmp_eq_u32_e32 vcc, 0, v71
	v_lshlrev_b32_e32 v65, 2, v65
	v_lshlrev_b32_e32 v64, 4, v64
	v_cndmask_b32_e64 v66, 0, 1, vcc
	v_lshlrev_b32_e32 v66, 3, v66
	v_cmp_eq_u32_e32 vcc, 0, v69
	v_or_b32_e32 v65, v66, v65
	s_nop 0
	v_cndmask_b32_e64 v66, 0, 1, vcc
	v_cmp_eq_u32_e32 vcc, 0, v68
	v_lshlrev_b32_e32 v66, 1, v66
	s_nop 0
	v_cndmask_b32_e64 v67, 0, 1, vcc
	v_or_b32_e32 v66, v67, v66
	v_and_b32_e32 v66, 3, v66
	v_or_b32_e32 v65, v66, v65
	v_and_b32_e32 v65, 15, v65
	v_or_b32_e32 v64, v65, v64
	v_cmp_eq_u32_sdwa s[0:1], v64, v81 src0_sel:BYTE_0 src1_sel:DWORD
	s_and_b64 vcc, exec, s[0:1]
	s_cbranch_vccnz .LBB0_742
	s_cmpk_eq_i32 s64, 0xffc0
	s_mov_b32 s0, 0
	s_waitcnt vmcnt(3)
	ds_write_b128 v111, v[16:19]
	s_waitcnt vmcnt(2)
	ds_write_b16 v112, v20 offset:17408
	ds_write_b16_d16_hi v112, v20 offset:17552
	ds_write_b16 v112, v21 offset:17696
	ds_write_b16_d16_hi v112, v21 offset:17840
	ds_write_b16 v112, v22 offset:17984
	ds_write_b16_d16_hi v112, v22 offset:18128
	ds_write_b16 v112, v23 offset:18272
	ds_write_b16_d16_hi v114, v23 offset:17408
	s_waitcnt vmcnt(1)
	ds_write_b128 v115, v[24:27]
	s_waitcnt vmcnt(0)
	ds_write_b16 v116, v36 offset:17408
	ds_write_b16_d16_hi v116, v36 offset:17552
	ds_write_b16 v116, v37 offset:17696
	ds_write_b16_d16_hi v116, v37 offset:17840
	ds_write_b16 v116, v38 offset:17984
	ds_write_b16_d16_hi v116, v38 offset:18128
	ds_write_b16 v116, v39 offset:18272
	ds_write_b16_d16_hi v117, v39 offset:17408
	s_cmp_lg_u32 s98, 0
	s_cbranch_scc1 .Latt2_skip
	s_mov_b32 s98, 1
	s_and_saveexec_b64 s[100:101], s[44:45]
	v_mov_b32_e32 v251, 1
	global_atomic_add v250, v81, v251, s[56:57] sc0
	s_or_b64 exec, exec, s[100:101]
.Latt2_skip:
	s_cmpk_eq_i32 s64, 0xffc0
	s_cbranch_scc1 .LBB0_746
	v_lshl_add_u64 v[16:17], v[92:93], 0, s[64:65]
	v_lshlrev_b64 v[16:17], 12, v[16:17]
	v_add_u32_e32 v80, s64, v83
	v_lshl_add_u64 v[24:25], v[90:91], 0, v[16:17]
	v_lshl_add_u64 v[16:17], s[66:67], 0, v[80:81]
	v_lshlrev_b64 v[16:17], 12, v[16:17]
	v_lshl_add_u64 v[26:27], s[68:69], 0, v[16:17]
	v_lshl_add_u64 v[36:37], v[86:87], 1, v[26:27]
	global_load_dwordx4 v[16:19], v[24:25], off
	global_load_dwordx4 v[20:23], v[36:37], off
	v_lshl_add_u64 v[24:25], v[94:95], 0, s[64:65]
	v_lshlrev_b64 v[24:25], 12, v[24:25]
	v_lshl_add_u64 v[64:65], v[90:91], 0, v[24:25]
	v_lshl_add_u64 v[66:67], v[88:89], 1, v[26:27]
	global_load_dwordx4 v[24:27], v[64:65], off
	global_load_dwordx4 v[36:39], v[66:67], off
	s_add_i32 s0, s64, 64

; __global__ void __launch_bounds__(NT) fwd_megakernel(Params pk) {
;   cg::grid_group grid = cg::this_grid();
;   Params* gp = (Params*)(pk.ws + OFF_PARAMS) + blockIdx.x;
;   if (threadIdx.x == 0) *gp = pk;
;   __syncthreads();
;   const Params& p = *gp;
;   xcd_barrier_register((unsigned*)(pk.ws + OFF_BAR));
;     ...
;   run_phase<0>(p); flat_barrier((unsigned*)(gp->ws + OFF_BAR));
;     ...
;   run_phase<0>(p);
;   if (pk.ws == nullptr) grid.sync();
;   flat_barrier((unsigned*)(gp->ws + OFF_BAR));
;   run_phase<1>(p); flat_barrier((unsigned*)(gp->ws + OFF_BAR));
;     ...
;   run_phase<102>(p); flat_barrier((unsigned*)(gp->ws + OFF_BAR));
;     ...
;   run_phase<2>(p); flat_barrier((unsigned*)(gp->ws + OFF_BAR));
;   run_phase<3>(p); flat_barrier((unsigned*)(gp->ws + OFF_BAR));
;   run_phase<13>(p); flat_barrier((unsigned*)(gp->ws + OFF_BAR));
;     ...
;   run_phase<104>(p); flat_barrier((unsigned*)(gp->ws + OFF_BAR));
;     ...
;   run_phase<4>(p); flat_barrier((unsigned*)(gp->ws + OFF_BAR));
;   run_phase<5>(p); flat_barrier((unsigned*)(gp->ws + OFF_BAR));
;   run_phase<6>(p); flat_barrier((unsigned*)(gp->ws + OFF_BAR));
;   run_phase<7>(p); flat_barrier((unsigned*)(gp->ws + OFF_BAR));
;     ...
;   run_phase<8>(p); flat_barrier((unsigned*)(gp->ws + OFF_BAR));
;     ...
;   run_phase<8>(p); flat_barrier((unsigned*)(gp->ws + OFF_BAR));
;   run_phase<9>(p); flat_barrier((unsigned*)(gp->ws + OFF_BAR));
;     ...
;   run_phase<10>(p); flat_barrier((unsigned*)(gp->ws + OFF_BAR));
;     ...
;   run_phase<10>(p); flat_barrier((unsigned*)(gp->ws + OFF_BAR));
;   run_phase<11>(p); flat_barrier((unsigned*)(gp->ws + OFF_BAR));
;   run_phase<12>(p);
; }
	.amdhsa_kernel _Z14fwd_megakernel6Params
		.amdhsa_group_segment_fixed_size 131072
		.amdhsa_private_segment_fixed_size 0
		.amdhsa_kernarg_size 424
		.amdhsa_user_sgpr_count 2
		.amdhsa_user_sgpr_dispatch_ptr 0
		.amdhsa_user_sgpr_queue_ptr 0
		.amdhsa_user_sgpr_kernarg_segment_ptr 1
		.amdhsa_user_sgpr_dispatch_id 0
		.amdhsa_user_sgpr_kernarg_preload_length 0
		.amdhsa_user_sgpr_kernarg_preload_offset 0
		.amdhsa_user_sgpr_private_segment_size 0
		.amdhsa_uses_dynamic_stack 0
		.amdhsa_enable_private_segment 0
		.amdhsa_system_sgpr_workgroup_id_x 1
		.amdhsa_system_sgpr_workgroup_id_y 0
		.amdhsa_system_sgpr_workgroup_id_z 0
		.amdhsa_system_sgpr_workgroup_info 0
		.amdhsa_system_vgpr_workitem_id 2
		.amdhsa_next_free_vgpr 256
		.amdhsa_next_free_sgpr 102
		.amdhsa_accum_offset 256
		.amdhsa_reserve_vcc 1
		.amdhsa_float_round_mode_32 0
		.amdhsa_float_round_mode_16_64 0
		.amdhsa_float_denorm_mode_32 3
		.amdhsa_float_denorm_mode_16_64 3
		.amdhsa_dx10_clamp 1
		.amdhsa_ieee_mode 1
		.amdhsa_fp16_overflow 0
		.amdhsa_tg_split 0
		.amdhsa_exception_fp_ieee_invalid_op 0
		.amdhsa_exception_fp_denorm_src 0
		.amdhsa_exception_fp_ieee_div_zero 0
		.amdhsa_exception_fp_ieee_overflow 0
		.amdhsa_exception_fp_ieee_underflow 0
		.amdhsa_exception_fp_ieee_inexact 0
		.amdhsa_exception_int_div_zero 0
	.end_amdhsa_kernel

; __global__ void __launch_bounds__(NT) fwd_megakernel(Params pk) {
;   cg::grid_group grid = cg::this_grid();
;   Params* gp = (Params*)(pk.ws + OFF_PARAMS) + blockIdx.x;
;   if (threadIdx.x == 0) *gp = pk;
;   __syncthreads();
;   const Params& p = *gp;
;   xcd_barrier_register((unsigned*)(pk.ws + OFF_BAR));
amdhsa.kernels:
  - .agpr_count:     0
    .args:
      - .offset:         0
        .size:           168
        .value_kind:     by_value
      - .offset:         168
        .size:           4
        .value_kind:     hidden_block_count_x
      - .offset:         172
        .size:           4
        .value_kind:     hidden_block_count_y
      - .offset:         176
        .size:           4
        .value_kind:     hidden_block_count_z
      - .offset:         180
        .size:           2
        .value_kind:     hidden_group_size_x
      - .offset:         182
        .size:           2
        .value_kind:     hidden_group_size_y
      - .offset:         184
        .size:           2
        .value_kind:     hidden_group_size_z
      - .offset:         186
        .size:           2
        .value_kind:     hidden_remainder_x
      - .offset:         188
        .size:           2
        .value_kind:     hidden_remainder_y
      - .offset:         190
        .size:           2
        .value_kind:     hidden_remainder_z
      - .offset:         208
        .size:           8
        .value_kind:     hidden_global_offset_x
      - .offset:         216
        .size:           8
        .value_kind:     hidden_global_offset_y
      - .offset:         224
        .size:           8
        .value_kind:     hidden_global_offset_z
      - .offset:         232
        .size:           2
        .value_kind:     hidden_grid_dims
      - .offset:         256
        .size:           8
        .value_kind:     hidden_multigrid_sync_arg
    .group_segment_fixed_size: 131072
    .kernarg_segment_align: 8
    .kernarg_segment_size: 424
    .language:       OpenCL C
    .language_version:
      - 2
      - 0
    .max_flat_workgroup_size: 512
    .name:           _Z14fwd_megakernel6Params
    .private_segment_fixed_size: 0
    .sgpr_count:     108
    .sgpr_spill_count: 4
    .symbol:         _Z14fwd_megakernel6Params.kd
    .uniform_work_group_size: 1
    .uses_dynamic_stack: false
    .vgpr_count:     256
    .vgpr_spill_count: 0
    .wavefront_size: 64
